# reversed mixer-prenorm row order, start row found by a scalar loop (no assumption on the grid size)
# speedup vs baseline: 1.0131x; 1.0014x over previous
.LBB0_424:
	s_ashr_i32 s3, s3, 6
	s_add_i32 s12, s3, s40
	s_cmpk_gt_i32 s12, 0x43ff
	v_readlane_b32 s33, v255, 4
	s_cbranch_scc1 .LBB0_442
	v_readlane_b32 s4, v255, 38
	s_add_u32 s4, s0, s4
	s_addc_u32 s5, s1, 0
	s_load_dwordx2 s[14:15], s[4:5], 0x0
	v_lshlrev_b32_e32 v0, 2, v2
	s_load_dwordx2 s[4:5], s[0:1], 0xc8
	s_waitcnt vmcnt(12)
	v_and_b32_e32 v34, 0xfc, v0
	v_lshlrev_b32_e32 v0, 2, v34
	v_and_b32_e32 v3, 64, v228
	v_add_u32_e32 v3, 64, v3
	s_waitcnt lgkmcnt(0)
	v_lshl_add_u64 v[4:5], s[4:5], 0, v[0:1]
	s_mov_b64 s[4:5], 0xbb00000
	v_lshl_add_u64 v[36:37], v[4:5], 0, s[4:5]
	v_xor_b32_e32 v4, 1, v228
	v_cmp_lt_i32_e32 vcc, v4, v3
	v_readlane_b32 s4, v255, 52
	v_readlane_b32 s5, v255, 53
	v_cndmask_b32_e32 v4, v228, v4, vcc
	v_lshlrev_b32_e32 v35, 2, v4
	v_xor_b32_e32 v4, 2, v228
	v_cmp_lt_i32_e32 vcc, v4, v3
	s_ashr_i32 s13, s12, 31
	v_lshl_add_u64 v[44:45], s[4:5], 0, v[0:1]
	v_cndmask_b32_e32 v4, v228, v4, vcc
	s_waitcnt vmcnt(8)
	v_lshlrev_b32_e32 v39, 2, v4
	v_xor_b32_e32 v4, 4, v228
	v_cmp_lt_i32_e32 vcc, v4, v3
	s_lshl_b64 s[4:5], s[12:13], 11
	v_readlane_b32 s8, v255, 54
	v_cndmask_b32_e32 v4, v228, v4, vcc
	v_lshlrev_b32_e32 v41, 2, v4
	v_xor_b32_e32 v4, 8, v228
	v_cmp_lt_i32_e32 vcc, v4, v3
	v_and_b32_e32 v0, 63, v2
	s_add_u32 s4, s8, s4
	v_cndmask_b32_e32 v4, v228, v4, vcc
	v_lshlrev_b32_e32 v43, 2, v4
	v_xor_b32_e32 v4, 16, v228
	v_cmp_lt_i32_e32 vcc, v4, v3
	v_readlane_b32 s8, v255, 55
	v_lshlrev_b32_e32 v0, 3, v0
	v_cndmask_b32_e32 v4, v228, v4, vcc
	s_addc_u32 s5, s8, s5
	v_lshlrev_b32_e32 v52, 2, v4
	v_xor_b32_e32 v4, 32, v228
	s_waitcnt vmcnt(4)
	v_lshl_add_u64 v[46:47], s[4:5], 0, v[0:1]
	v_readlane_b32 s4, v254, 47
	v_cmp_lt_i32_e32 vcc, v4, v3
	s_add_i32 s3, s4, s3
	s_lshl_b32 s3, s3, 10
	v_cndmask_b32_e32 v3, v228, v4, vcc
	v_or_b32_e32 v38, 0x100, v34
	v_or_b32_e32 v40, 0x200, v34
	v_or_b32_e32 v42, 0x300, v34
	v_lshlrev_b32_e32 v53, 2, v3
	s_add_i32 s4, s3, 0xff000000
	s_mov_b64 s[16:17], 0
	v_lshlrev_b32_e32 v0, 2, v34
	s_mov_b32 s3, s12
	s_mov_b32 s8, 0
.Lpnrev_fwd:
	s_add_i32 s9, s3, s30
	s_cmpk_gt_i32 s9, 0x43ff
	s_cbranch_scc1 .Lpnrev_fwd_done
	s_mov_b32 s3, s9
	s_add_i32 s8, s8, 1
	s_branch .Lpnrev_fwd
.Lpnrev_fwd_done:
	s_mul_i32 s16, s8, s30
	s_mul_hi_u32 s17, s8, s30
	s_mul_i32 s9, s8, s31
	s_add_i32 s17, s17, s9
	s_mul_i32 s9, s8, s33
	s_add_i32 s4, s4, s9
	v_readlane_b32 s20, v254, 60
	v_readlane_b32 s21, v254, 61
	s_nop 0
	s_mul_i32 s9, s8, s21
	s_mul_hi_u32 s21, s8, s20
	s_add_i32 s21, s21, s9
	s_mul_i32 s20, s8, s20
	s_nop 0
	v_lshl_add_u64 v[46:47], v[46:47], 0, s[20:21]
	s_branch .LBB0_427
